# k47: k44 + attention staging instruction selection (cross-row logf prefix via three VALU ops on per-lane row masks instead of nested exec-masked blocks; SALU mask instead of VALU re-materialisation)
# speedup vs baseline: 1.0192x; 1.0164x over previous
; #define LAS __attribute__((address_space(3)))
; #define ATT_GLD16(dst, ptr) asm volatile("global_load_dwordx4 %0, %1, off" : "=&v"(dst) : "v"(ptr) : "memory")
; __device__ __forceinline__ void attn_unit(const UnitDesc& u, LAS unsigned char* shm, float qkmax, float thresh) {
;     int tid_ = threadIdx.x; asm volatile("" : "+v"(tid_));
;     const int tid = tid_, lane = tid & 63, r32 = lane & 31, hi = lane >> 5; const int wid = __builtin_amdgcn_readfirstlane(tid >> 6);
;     const int NT = (u.q0 + u.nq) >> 6, nband = u.nq >> 6;
;     const bool active = wid * 32 < u.nq;
;     LAS float* wsf = (LAS float*)(shm + LDS_WS) + wid * 128;
;     const bf16_t* ksrc = u.K + (size_t)lane * 512 + wid * 8;
;     const bf16_t* vsrc = u.V + (size_t)(16 * (wid & 3) + (lane >> 2)) * 512 + (wid >> 2) * 32 + (lane & 3) * 8;
;     const float* lsrc = u.LF + (size_t)lane * 8;
;     LAS unsigned char* kdst = shm + LDS_K + wid * 1024 + lane * 16;
;     LAS unsigned char* vdst = shm + LDS_V + wid * 1024 + lane * 16;
;     const int vb0 = (int)(unsigned)(uintptr_t)(shm + LDS_V) + ((lane >> 4) & 1) * 32 + (lane & 3) * 8 + (4 * hi + ((lane & 15) >> 2)) * 64;
;     const LAS unsigned char* kb = shm + LDS_K + hi * 1024 + r32 * 16;
;     ...
;     u32x4 kreg = *(const u32x4*)(ksrc + (size_t)(NT - 1) * 64 * 512), vreg = *(const u32x4*)(vsrc + (size_t)(NT - 1) * 64 * 512);
;     float lfb[4];
; #pragma unroll
;     for (int jb = 0; jb < 4; ++jb) { const int tile = NT - 1 - jb; lfb[jb] = lsrc[(size_t)(tile > 0 ? tile : 0) * 64 * 8]; }
;     u32x4 kA, vA, kB, vB, kC, vC;
;     { const int t2 = NT >= 2 ? NT - 2 : 0, t3 = NT >= 3 ? NT - 3 : 0, t4 = NT >= 4 ? NT - 4 : 0;
;       ATT_GLD16(kA, ksrc + (size_t)t2 * 64 * 512); ATT_GLD16(vA, vsrc + (size_t)t2 * 64 * 512);
;       ATT_GLD16(kB, ksrc + (size_t)t3 * 64 * 512); ATT_GLD16(vB, vsrc + (size_t)t3 * 64 * 512);
;       ATT_GLD16(kC, ksrc + (size_t)t4 * 64 * 512); ATT_GLD16(vC, vsrc + (size_t)t4 * 64 * 512); }
;     bf16x8 qr[4];
; #pragma unroll
;     for (int d0 = 0; d0 < 4; ++d0) qr[d0] = (bf16x8){0, 0, 0, 0, 0, 0, 0, 0};
;     if (active) { const bf16_t* Qw = u.Q + (size_t)(wid * 32 + r32) * 512;
; #pragma unroll
;         for (int d0 = 0; d0 < 4; ++d0) qr[d0] = *(const bf16x8*)(Qw + d0 * 16 + hi * 8); }
.LBB0_731:
	s_lshl_b64 s[48:49], s[28:29], 2
	v_mov_b32_e32 v12, v208
	s_add_u32 s12, s12, s48
	s_addc_u32 s13, s13, s49
	v_and_b32_e32 v137, 63, v12
	v_cmp_gt_u32_e64 s[100:101], 16, v137
	s_nop 1
	v_cndmask_b32_e64 v191, 0, 1.0, s[100:101]
	v_cmp_gt_u32_e64 s[100:101], 32, v137
	s_nop 1
	v_cndmask_b32_e64 v192, 0, 1.0, s[100:101]
	v_cmp_gt_u32_e64 s[100:101], 48, v137
	s_nop 1
	v_cndmask_b32_e64 v193, 0, 1.0, s[100:101]
	v_readfirstlane_b32 s68, v12
	s_ashr_i32 s52, s68, 6
	v_lshlrev_b32_e32 v0, 10, v137
	v_lshl_add_u64 v[2:3], s[10:11], 0, v[0:1]
	s_lshl_b32 s10, s52, 3
	s_ashr_i32 s11, s10, 31
	v_lshl_add_u64 v[106:107], s[10:11], 1, v[2:3]
	s_lshl_b32 s10, s52, 4
	v_bfe_u32 v0, v12, 2, 4
	v_and_or_b32 v0, s10, 48, v0
	v_lshlrev_b32_e32 v0, 10, v0
	s_add_i32 s28, s53, s66
	v_lshl_add_u64 v[2:3], s[8:9], 0, v[0:1]
	s_ashr_i32 s8, s68, 3
	s_ashr_i32 s67, s28, 6
	s_andn2_b32 s8, s8, 31
	v_lshlrev_b32_e32 v138, 3, v12
	s_ashr_i32 s9, s8, 31
	v_and_b32_e32 v13, 24, v138
	s_add_i32 s48, s67, -1
	v_lshl_add_u64 v[2:3], s[8:9], 1, v[2:3]
	v_lshlrev_b32_e32 v0, 1, v13
	s_ashr_i32 s49, s48, 31
	v_lshl_add_u64 v[108:109], v[2:3], 0, v[0:1]
	v_lshlrev_b32_e32 v0, 5, v137
	s_lshl_b64 s[8:9], s[48:49], 16
	s_max_i32 s28, s48, 0
	v_lshl_add_u64 v[110:111], s[12:13], 0, v[0:1]
	v_lshl_add_u64 v[2:3], v[106:107], 0, s[8:9]
	v_lshl_add_u64 v[6:7], v[108:109], 0, s[8:9]
	s_lshl_b64 s[8:9], s[28:29], 11
	v_lshl_add_u64 v[10:11], v[110:111], 0, s[8:9]
	s_max_i32 s8, s67, 2
	s_add_i32 s28, s8, -2
	s_lshl_b64 s[8:9], s[28:29], 11
	v_lshl_add_u64 v[16:17], v[110:111], 0, s[8:9]
	s_max_i32 s8, s67, 3
	s_add_i32 s8, s8, -3
	s_mov_b32 s9, s29
	s_lshl_b64 s[10:11], s[8:9], 11
	v_lshl_add_u64 v[18:19], v[110:111], 0, s[10:11]
	s_max_i32 s10, s67, 4
	s_add_i32 s10, s10, -4
	s_mov_b32 s11, s29
	s_lshl_b64 s[12:13], s[10:11], 11
	v_lshl_add_u64 v[20:21], v[110:111], 0, s[12:13]
	global_load_dword v14, v[10:11], off
	global_load_dword v140, v[16:17], off
	global_load_dword v141, v[18:19], off
	global_load_dword v139, v[20:21], off
	global_load_dwordx4 v[2:5], v[2:3], off
	global_load_dwordx4 v[6:9], v[6:7], off
	s_lshl_b32 s49, s52, 5
	s_cmp_lt_i32 s49, s53
	s_cselect_b64 s[58:59], -1, 0
	s_cmp_ge_i32 s49, s53
	s_cselect_b64 s[60:61], -1, 0
	v_and_b32_e32 v135, 31, v12
	v_bfe_u32 v136, v12, 5, 1
	s_and_b64 vcc, exec, s[60:61]
	v_or_b32_e32 v10, s49, v135
	s_cbranch_vccnz .LBB0_733
	v_ashrrev_i32_e32 v11, 31, v10
	v_lshlrev_b64 v[16:17], 10, v[10:11]
	v_lshl_add_u64 v[16:17], s[6:7], 0, v[16:17]
	v_lshlrev_b32_e32 v0, 4, v136
	v_lshl_add_u64 v[16:17], v[16:17], 0, v[0:1]
	global_load_dwordx4 v[94:97], v[16:17], off
	global_load_dwordx4 v[98:101], v[16:17], off offset:32
	global_load_dwordx4 v[102:105], v[16:17], off offset:64
	global_load_dwordx4 v[90:93], v[16:17], off offset:96
	s_branch .LBB0_734

; #define DPP_SHL(v, n) __builtin_bit_cast(float, __builtin_amdgcn_update_dpp(0, __builtin_bit_cast(int, (v)), 0x100 | (n), 0xF, 0xF, true))
; __device__ __forceinline__ float suffix_incl(float v, int lane) {
;     v += DPP_SHL(v, 1); v += DPP_SHL(v, 2); v += DPP_SHL(v, 4); v += DPP_SHL(v, 8);
;     const float t1 = __builtin_bit_cast(float, __builtin_amdgcn_readlane(__builtin_bit_cast(int, v), 16)), t2 = __builtin_bit_cast(float, __builtin_amdgcn_readlane(__builtin_bit_cast(int, v), 32)),
;                 t3 = __builtin_bit_cast(float, __builtin_amdgcn_readlane(__builtin_bit_cast(int, v), 48));
;     const int row = lane >> 4;
;     const float add = (row == 0) ? (t1 + t2) + t3 : (row == 1) ? t2 + t3 : (row == 2) ? t3 : 0.f;
;     return v + add;
.LBB0_777:
	s_waitcnt lgkmcnt(0)
	s_barrier
	s_waitcnt vmcnt(8)
	s_nop 1
	v_add_f32_dpp v0, v140, v140 row_shl:1 row_mask:0xf bank_mask:0xf bound_ctrl:1
	s_nop 1
	v_add_f32_dpp v0, v0, v0 row_shl:2 row_mask:0xf bank_mask:0xf bound_ctrl:1
	s_nop 1
	v_add_f32_dpp v0, v0, v0 row_shl:4 row_mask:0xf bank_mask:0xf bound_ctrl:1
	s_nop 1
	v_add_f32_dpp v0, v0, v0 row_shl:8 row_mask:0xf bank_mask:0xf bound_ctrl:1
	s_nop 0
	v_readlane_b32 s28, v0, 16
	v_readlane_b32 s67, v0, 32
	v_readlane_b32 s66, v0, 48
	s_nop 0
	v_mul_f32_e32 v149, s67, v192
	v_fmac_f32_e32 v149, s28, v191
	v_fmac_f32_e32 v149, s66, v193
	v_add_f32_e32 v149, v0, v149
	s_xor_b32 s74, s70, 1
	v_add_f32_e32 v0, v150, v149
	s_lshl_b32 s12, s74, 8
	v_sub_f32_e32 v0, v0, v140
	s_add_i32 s71, s53, s12
	s_lshl_b32 s78, s74, 14
	s_max_i32 s12, s48, 4
	v_mul_f32_e32 v140, 0x3fb8aa3b, v0
	v_lshl_add_u32 v0, v137, 2, s71
	v_readfirstlane_b32 s76, v149
	v_add_u32_e32 v149, s78, v143
	s_add_i32 s28, s12, -4
	ds_write_b32 v0, v140 offset:32768
	s_waitcnt vmcnt(4)
	ds_write_b128 v149, v[66:69]
	ds_write_b128 v149, v[74:77] offset:8192
	s_lshl_b64 s[12:13], s[28:29], 11
	s_waitcnt lgkmcnt(0)
	v_lshl_add_u64 v[66:67], v[110:111], 0, s[12:13]
	s_lshl_b64 s[12:13], s[28:29], 16
	global_load_dword v140, v[66:67], off
	v_lshl_add_u64 v[74:75], v[106:107], 0, s[12:13]
	global_load_dwordx4 v[66:69], v[74:75], off
	s_nop 0
	v_lshl_add_u64 v[152:153], v[108:109], 0, s[12:13]
	s_not_b64 s[12:13], s[58:59]
	global_load_dwordx4 v[74:77], v[152:153], off
	s_andn2_b64 vcc, exec, s[58:59]
	s_cbranch_vccnz .LBB0_792
	s_and_b64 vcc, exec, s[98:99]
	s_cbranch_vccnz .LBB0_792
	s_sub_i32 s28, s75, 64
	s_cmp_gt_i32 s28, s73
	s_cbranch_scc1 .LBB0_792
	s_lshl_b32 s64, s70, 8
	s_lshl_b32 s28, s70, 14
	s_add_i32 s66, s53, s64
	s_cmp_lt_i32 s48, s72
	v_add_u32_e32 v151, s28, v144
	s_mov_b64 s[64:65], -1
	v_add_u32_e32 v152, s28, v145
	v_lshl_add_u32 v153, v142, 2, s66
	s_cbranch_scc1 .LBB0_789
	ds_read_b128 v[34:37], v153 offset:32768
	ds_read_b128 v[38:41], v153 offset:32800
	ds_read_b128 v[42:45], v153 offset:32832
	ds_read_b128 v[46:49], v153 offset:32864
	ds_read_b128 v[50:53], v153 offset:32896
	ds_read_b128 v[54:57], v153 offset:32928
	ds_read_b128 v[58:61], v153 offset:32960
	ds_read_b128 v[62:65], v153 offset:32992
	ds_read_b128 v[154:157], v152
	ds_read_b128 v[158:161], v152 offset:512
	s_waitcnt lgkmcnt(4)
	ds_read_b128 v[210:213], v152 offset:2048
	ds_read_b128 v[214:217], v152 offset:2560
	ds_read_b128 v[218:221], v152 offset:4096
	ds_read_b128 v[222:225], v152 offset:4608
	ds_read_b128 v[226:229], v152 offset:6656
	ds_read_b128 v[230:233], v152 offset:6144
	v_pk_add_f32 v[56:57], v[118:119], v[56:57]
	s_waitcnt lgkmcnt(9)
	v_pk_add_f32 v[60:61], v[122:123], v[60:61]
	s_waitcnt lgkmcnt(8)
	v_pk_add_f32 v[64:65], v[126:127], v[64:65]
	v_pk_add_f32 v[52:53], v[114:115], v[52:53]
	v_pk_add_f32 v[62:63], v[124:125], v[62:63]
	v_pk_add_f32 v[58:59], v[120:121], v[58:59]
	v_pk_add_f32 v[54:55], v[116:117], v[54:55]
	v_pk_add_f32 v[50:51], v[112:113], v[50:51]
	v_pk_add_f32 v[48:49], v[126:127], v[48:49]
	v_pk_add_f32 v[44:45], v[122:123], v[44:45]
	v_pk_add_f32 v[40:41], v[118:119], v[40:41]
	v_pk_add_f32 v[36:37], v[114:115], v[36:37]
	v_pk_add_f32 v[46:47], v[124:125], v[46:47]
	v_pk_add_f32 v[42:43], v[120:121], v[42:43]
	v_pk_add_f32 v[38:39], v[116:117], v[38:39]
	v_pk_add_f32 v[34:35], v[112:113], v[34:35]
	s_waitcnt lgkmcnt(6)
	v_mfma_f32_32x32x16_bf16 v[50:65], v[158:161], v[94:97], v[50:65]
	v_mfma_f32_32x32x16_bf16 v[34:49], v[154:157], v[94:97], v[34:49]
	s_waitcnt lgkmcnt(4)
	v_mfma_f32_32x32x16_bf16 v[50:65], v[214:217], v[98:101], v[50:65]
	v_mfma_f32_32x32x16_bf16 v[34:49], v[210:213], v[98:101], v[34:49]
	s_waitcnt lgkmcnt(2)
	v_mfma_f32_32x32x16_bf16 v[50:65], v[222:225], v[102:105], v[50:65]
	v_mfma_f32_32x32x16_bf16 v[34:49], v[218:221], v[102:105], v[34:49]
	s_waitcnt lgkmcnt(1)
	v_mfma_f32_32x32x16_bf16 v[50:65], v[226:229], v[90:93], v[50:65]
	v_add_u32_e32 v154, s75, v142
	v_subrev_u32_e32 v156, 32, v154
	v_subrev_u32_e32 v155, 64, v154
	v_cmp_le_i32_e32 vcc, v156, v147
	s_waitcnt lgkmcnt(0)
; __device__ __forceinline__ unsigned cvtpk(float lo, float hi) { typedef __bf16 bf16x2_t __attribute__((ext_vector_type(2))); f32x2 v = {lo, hi}; bf16x2_t b = __builtin_convertvector(v, bf16x2_t); return __builtin_bit_cast(unsigned, b); }
; template <bool BAND>
; __device__ __forceinline__ void tile_body(f32x16* o, float& l_reg, const bf16x8* qr, const LAS unsigned char* kbs, const LAS float* wb, int vb, float ci, int hi, int keybase, int qabs) {
;     ...
;     if (BAND) {
; #pragma unroll
;         for (int r = 0; r < 16; ++r) { const int key = keybase + 8 * (r >> 2) + (r & 3); if (key > qabs) p0[r] = -INFINITY; if (key + 32 > qabs) p1[r] = -INFINITY; }
;     }
;     f32x2 s2 = {0.f, 0.f};
; #pragma unroll
;     for (int r = 0; r < 16; r += 2) {
;         p0[r] = __builtin_amdgcn_exp2f(p0[r]); p0[r + 1] = __builtin_amdgcn_exp2f(p0[r + 1]); p1[r] = __builtin_amdgcn_exp2f(p1[r]); p1[r + 1] = __builtin_amdgcn_exp2f(p1[r + 1]);
;         s2 += (f32x2){p0[r], p0[r + 1]}; s2 += (f32x2){p1[r], p1[r + 1]}; }
;     l_reg += s2.x + s2.y;
;     u32x4 pw0, pw1, pw2, pw3;
;     pw0 = (u32x4){cvtpk(p0[0], p0[1]), cvtpk(p0[2], p0[3]), cvtpk(p0[4], p0[5]), cvtpk(p0[6], p0[7])};
;     pw1 = (u32x4){cvtpk(p0[8], p0[9]), cvtpk(p0[10], p0[11]), cvtpk(p0[12], p0[13]), cvtpk(p0[14], p0[15])};
;     pw2 = (u32x4){cvtpk(p1[0], p1[1]), cvtpk(p1[2], p1[3]), cvtpk(p1[4], p1[5]), cvtpk(p1[6], p1[7])};
;     pw3 = (u32x4){cvtpk(p1[8], p1[9]), cvtpk(p1[10], p1[11]), cvtpk(p1[12], p1[13]), cvtpk(p1[14], p1[15])};
;     pv(o, vb, __builtin_bit_cast(bf16x8, pw0), __builtin_bit_cast(bf16x8, pw1), __builtin_bit_cast(bf16x8, pw2), __builtin_bit_cast(bf16x8, pw3));
	v_mfma_f32_32x32x16_bf16 v[34:49], v[230:233], v[90:93], v[34:49]
	s_nop 5
	v_cndmask_b32_e32 v50, v134, v50, vcc
	v_cmp_lt_i32_e32 vcc, v155, v147
	s_nop 3
	v_cndmask_b32_e32 v35, v134, v35, vcc
	v_cmp_le_i32_e32 vcc, v155, v147
	v_subrev_u32_e32 v155, 31, v154
	v_exp_f32_e32 v35, v35
	v_cndmask_b32_e32 v34, v134, v34, vcc
	v_cmp_le_i32_e32 vcc, v155, v147
	v_subrev_u32_e32 v155, 62, v154
	v_exp_f32_e32 v34, v34
	v_cndmask_b32_e32 v51, v134, v51, vcc
	v_cmp_le_i32_e32 vcc, v155, v147
	s_nop 1
	v_cndmask_b32_e32 v155, v134, v36, vcc
	v_subrev_u32_e32 v36, 30, v154
	v_cmp_le_i32_e32 vcc, v36, v147
	v_subrev_u32_e32 v36, 61, v154
	s_nop 0
	v_cndmask_b32_e32 v52, v134, v52, vcc
	v_cmp_le_i32_e32 vcc, v36, v147
	v_subrev_u32_e32 v36, 29, v154
	s_nop 0
	v_cndmask_b32_e32 v156, v134, v37, vcc
	v_cmp_le_i32_e32 vcc, v36, v147
	v_subrev_u32_e32 v36, 56, v154
	v_exp_f32_e32 v37, v51
	v_cndmask_b32_e32 v53, v134, v53, vcc
	v_cmp_le_i32_e32 vcc, v36, v147
	v_subrev_u32_e32 v36, 24, v154
	s_nop 0
	v_cndmask_b32_e32 v157, v134, v38, vcc
	v_cmp_le_i32_e32 vcc, v36, v147
	v_subrev_u32_e32 v36, 55, v154
	v_exp_f32_e32 v38, v155
	v_cndmask_b32_e32 v54, v134, v54, vcc
	v_cmp_le_i32_e32 vcc, v36, v147
	v_subrev_u32_e32 v36, 23, v154
	s_nop 0
	v_cndmask_b32_e32 v158, v134, v39, vcc
	v_cmp_le_i32_e32 vcc, v36, v147
	v_subrev_u32_e32 v36, 54, v154
	v_exp_f32_e32 v39, v156
	v_cndmask_b32_e32 v55, v134, v55, vcc
	v_cmp_le_i32_e32 vcc, v36, v147
	v_subrev_u32_e32 v36, 22, v154
	v_cvt_pk_bf16_f32 v156, v34, v35
	v_cndmask_b32_e32 v159, v134, v40, vcc
	v_cmp_le_i32_e32 vcc, v36, v147
	v_subrev_u32_e32 v36, 53, v154
	v_exp_f32_e32 v40, v52
	v_cndmask_b32_e32 v56, v134, v56, vcc
	v_cmp_le_i32_e32 vcc, v36, v147
	v_subrev_u32_e32 v36, 21, v154
	s_nop 0
	v_cndmask_b32_e32 v160, v134, v41, vcc
	v_cmp_le_i32_e32 vcc, v36, v147
	v_subrev_u32_e32 v36, 48, v154
	v_exp_f32_e32 v41, v53
	v_cndmask_b32_e32 v57, v134, v57, vcc
	v_cmp_le_i32_e32 vcc, v36, v147
	v_add_u32_e32 v36, -16, v154
	v_exp_f32_e32 v51, v57
	v_cndmask_b32_e32 v161, v134, v42, vcc
	v_cmp_le_i32_e32 vcc, v36, v147
	v_subrev_u32_e32 v36, 47, v154
	v_exp_f32_e32 v52, v161
	v_cndmask_b32_e32 v58, v134, v58, vcc
	v_cmp_le_i32_e32 vcc, v36, v147
	v_add_u32_e32 v36, -15, v154
	s_nop 0
	v_cndmask_b32_e32 v162, v134, v43, vcc
	v_cmp_le_i32_e32 vcc, v36, v147
	v_subrev_u32_e32 v36, 46, v154
	v_pk_add_f32 v[42:43], v[34:35], 0 op_sel_hi:[1,0]
	v_cndmask_b32_e32 v59, v134, v59, vcc
	v_cmp_le_i32_e32 vcc, v36, v147
	v_add_u32_e32 v36, -14, v154
	v_exp_f32_e32 v53, v162
	v_cndmask_b32_e32 v163, v134, v44, vcc
	v_cmp_le_i32_e32 vcc, v36, v147
	v_subrev_u32_e32 v36, 45, v154
	v_exp_f32_e32 v44, v157
	v_cndmask_b32_e32 v60, v134, v60, vcc
	v_cmp_le_i32_e32 vcc, v36, v147
	v_add_u32_e32 v36, -13, v154
	v_cvt_pk_bf16_f32 v157, v38, v39
	v_cndmask_b32_e32 v164, v134, v45, vcc
	v_cmp_le_i32_e32 vcc, v36, v147
	v_subrev_u32_e32 v36, 40, v154
	v_exp_f32_e32 v45, v158
	v_cndmask_b32_e32 v61, v134, v61, vcc
	v_cmp_le_i32_e32 vcc, v36, v147
	v_add_u32_e32 v36, -8, v154
	v_exp_f32_e32 v57, v164
	v_cndmask_b32_e32 v165, v134, v46, vcc
	v_cmp_le_i32_e32 vcc, v36, v147
	v_subrev_u32_e32 v36, 39, v154
	v_exp_f32_e32 v46, v54
	v_cndmask_b32_e32 v62, v134, v62, vcc
	v_cmp_le_i32_e32 vcc, v36, v147
	v_add_u32_e32 v36, -7, v154
	v_exp_f32_e32 v54, v58
	v_cndmask_b32_e32 v166, v134, v47, vcc
	v_cmp_le_i32_e32 vcc, v36, v147
	v_subrev_u32_e32 v36, 38, v154
	v_exp_f32_e32 v47, v55
	v_cndmask_b32_e32 v63, v134, v63, vcc
	v_cmp_le_i32_e32 vcc, v36, v147
	v_add_u32_e32 v36, -6, v154
	v_exp_f32_e32 v55, v59
	v_cndmask_b32_e32 v167, v134, v48, vcc
	v_cmp_le_i32_e32 vcc, v36, v147
	v_subrev_u32_e32 v36, 37, v154
	v_exp_f32_e32 v48, v159
	v_cndmask_b32_e32 v168, v134, v64, vcc
	v_cmp_le_i32_e32 vcc, v36, v147
	v_add_u32_e32 v36, -5, v154
	v_exp_f32_e32 v58, v60
	v_cndmask_b32_e32 v169, v134, v49, vcc
	v_cmp_le_i32_e32 vcc, v36, v147
	v_exp_f32_e32 v36, v50
	v_exp_f32_e32 v49, v160
	v_exp_f32_e32 v50, v56
	v_exp_f32_e32 v56, v163
	v_pk_add_f32 v[42:43], v[36:37], v[42:43]
	v_exp_f32_e32 v59, v61
	v_pk_add_f32 v[42:43], v[38:39], v[42:43]
	v_exp_f32_e32 v64, v167
	v_pk_add_f32 v[42:43], v[40:41], v[42:43]
	v_cvt_pk_bf16_f32 v167, v50, v51
	v_pk_add_f32 v[42:43], v[44:45], v[42:43]
	v_exp_f32_e32 v60, v165
	v_pk_add_f32 v[42:43], v[46:47], v[42:43]
	v_exp_f32_e32 v61, v166
	v_pk_add_f32 v[42:43], v[48:49], v[42:43]
	v_cvt_pk_bf16_f32 v160, v52, v53
	v_pk_add_f32 v[42:43], v[50:51], v[42:43]
	ds_read_b64_tr_b16 v[50:51],v151 offset:0
	v_exp_f32_e32 v62, v62
	v_pk_add_f32 v[42:43], v[52:53], v[42:43]
	ds_read_b64_tr_b16 v[52:53],v151 offset:512
	v_exp_f32_e32 v63, v63
	v_pk_add_f32 v[42:43], v[54:55], v[42:43]
	v_exp_f32_e32 v172, v168
	v_cvt_pk_bf16_f32 v168, v54, v55
	ds_read_b64_tr_b16 v[54:55],v151 offset:1024
	v_cndmask_b32_e32 v154, v134, v65, vcc
	v_pk_add_f32 v[42:43], v[56:57], v[42:43]
	v_exp_f32_e32 v65, v169
	v_cvt_pk_bf16_f32 v161, v56, v57
	ds_read_b64_tr_b16 v[56:57],v151 offset:1536
	v_pk_add_f32 v[42:43], v[58:59], v[42:43]
	v_exp_f32_e32 v173, v154
	v_cvt_pk_bf16_f32 v169, v58, v59
	ds_read_b64_tr_b16 v[58:59],v151 offset:2048
	v_pk_add_f32 v[42:43], v[60:61], v[42:43]
	v_cvt_pk_bf16_f32 v162, v60, v61
	ds_read_b64_tr_b16 v[60:61],v151 offset:2560
	v_pk_add_f32 v[42:43], v[62:63], v[42:43]
	v_cvt_pk_bf16_f32 v170, v62, v63
	ds_read_b64_tr_b16 v[62:63],v151 offset:3072
	v_pk_add_f32 v[42:43], v[64:65], v[42:43]
	v_cvt_pk_bf16_f32 v163, v64, v65
	ds_read_b64_tr_b16 v[64:65],v151 offset:3584
	v_pk_add_f32 v[42:43], v[172:173], v[42:43]
	s_waitcnt lgkmcnt(0)
	v_cvt_pk_bf16_f32 v158, v44, v45
	v_add_f32_e32 v42, v42, v43
	v_add_f32_e32 v154, v148, v42
	v_cvt_pk_bf16_f32 v159, v48, v49
	v_cvt_pk_bf16_f32 v164, v36, v37
	v_cvt_pk_bf16_f32 v165, v40, v41
	v_cvt_pk_bf16_f32 v166, v46, v47
	v_cvt_pk_bf16_f32 v171, v172, v173
	v_mfma_f32_32x32x16_bf16 v[2:17], v[156:159], v[50:53], v[2:17]
	ds_read_b64_tr_b16 v[172:173],v151 offset:4096
	ds_read_b64_tr_b16 v[174:175],v151 offset:4608
	ds_read_b64_tr_b16 v[176:177],v151 offset:5120
	ds_read_b64_tr_b16 v[178:179],v151 offset:5632
	ds_read_b64_tr_b16 v[180:181],v151 offset:6144
	ds_read_b64_tr_b16 v[182:183],v151 offset:6656
	ds_read_b64_tr_b16 v[184:185],v151 offset:7168
	v_mfma_f32_32x32x16_bf16 v[2:17], v[160:163], v[54:57], v[2:17]
	ds_read_b64_tr_b16 v[186:187],v151 offset:7680
	s_waitcnt lgkmcnt(0)
	v_mfma_f32_32x32x16_bf16 v[2:17], v[164:167], v[58:61], v[2:17]
	v_mfma_f32_32x32x16_bf16 v[2:17], v[168:171], v[62:65], v[2:17]
	v_mfma_f32_32x32x16_bf16 v[18:33], v[156:159], v[172:175], v[18:33]
	s_mov_b64 s[64:65], 0
	v_mfma_f32_32x32x16_bf16 v[18:33], v[160:163], v[176:179], v[18:33]
	v_mfma_f32_32x32x16_bf16 v[18:33], v[164:167], v[180:183], v[18:33]
	v_mfma_f32_32x32x16_bf16 v[18:33], v[168:171], v[184:187], v[18:33]

; #define DPP_SHL(v, n) __builtin_bit_cast(float, __builtin_amdgcn_update_dpp(0, __builtin_bit_cast(int, (v)), 0x100 | (n), 0xF, 0xF, true))
; __device__ __forceinline__ float suffix_incl(float v, int lane) {
;     v += DPP_SHL(v, 1); v += DPP_SHL(v, 2); v += DPP_SHL(v, 4); v += DPP_SHL(v, 8);
;     const float t1 = __builtin_bit_cast(float, __builtin_amdgcn_readlane(__builtin_bit_cast(int, v), 16)), t2 = __builtin_bit_cast(float, __builtin_amdgcn_readlane(__builtin_bit_cast(int, v), 32)),
;                 t3 = __builtin_bit_cast(float, __builtin_amdgcn_readlane(__builtin_bit_cast(int, v), 48));
;     const int row = lane >> 4;
;     const float add = (row == 0) ? (t1 + t2) + t3 : (row == 1) ? t2 + t3 : (row == 2) ? t3 : 0.f;
;     return v + add;
.LBB0_792:
	s_cmp_lg_u32 s48, 0
	v_fma_f32 v151, v150, s50, -v146
	s_cselect_b64 s[64:65], -1, 0
	v_cmp_nlt_f32_e64 s[66:67], v151, -v131
	v_fma_f32 v196, v150, s50, -v197
	v_cmp_lt_f32_e64 s[100:101], v196, -v131
	s_nop 3
	s_or_b64 s[98:99], s[98:99], s[100:101]
	s_and_b64 s[68:69], s[64:65], s[66:67]
	s_mov_b64 s[66:67], -1
	s_and_saveexec_b64 s[64:65], s[68:69]
	s_cbranch_execz .LBB0_776
	s_waitcnt lgkmcnt(0)
	s_barrier
	s_waitcnt vmcnt(8)
	s_nop 1
	v_add_f32_dpp v151, v141, v141 row_shl:1 row_mask:0xf bank_mask:0xf bound_ctrl:1
	s_nop 1
	v_add_f32_dpp v151, v151, v151 row_shl:2 row_mask:0xf bank_mask:0xf bound_ctrl:1
	s_nop 1
	v_add_f32_dpp v151, v151, v151 row_shl:4 row_mask:0xf bank_mask:0xf bound_ctrl:1
	s_nop 1
	v_add_f32_dpp v152, v151, v151 row_shl:8 row_mask:0xf bank_mask:0xf bound_ctrl:1
	s_nop 0
	v_readlane_b32 s28, v152, 16
	v_readlane_b32 s79, v152, 32
	v_readlane_b32 s77, v152, 48
	s_nop 0
	v_mul_f32_e32 v153, s79, v192
	v_fmac_f32_e32 v153, s28, v191
	v_fmac_f32_e32 v153, s77, v193
	v_add_f32_e32 v151, s76, v150
	v_add_f32_e32 v150, v152, v153
	v_add_f32_e32 v152, v151, v150
	s_lshl_b32 s28, s70, 8
	v_sub_f32_e32 v141, v152, v141
	s_add_i32 s76, s53, s28
	v_mul_f32_e32 v141, 0x3fb8aa3b, v141
	v_lshl_add_u32 v152, v137, 2, s76
	s_lshl_b32 s77, s70, 14
	ds_write_b32 v152, v141 offset:32768
	v_add_u32_e32 v141, s77, v143
	s_max_i32 s28, s48, 5
	s_waitcnt vmcnt(4)
	ds_write_b128 v141, v[70:73]
	ds_write_b128 v141, v[82:85] offset:8192
	s_add_i32 s28, s28, -5
	s_waitcnt lgkmcnt(0)
	s_lshl_b64 s[66:67], s[28:29], 11
	v_lshl_add_u64 v[70:71], v[110:111], 0, s[66:67]
	global_load_dword v141, v[70:71], off
	s_lshl_b64 s[66:67], s[28:29], 16
	v_lshl_add_u64 v[82:83], v[106:107], 0, s[66:67]
	global_load_dwordx4 v[70:73], v[82:83], off
	v_lshl_add_u64 v[152:153], v[108:109], 0, s[66:67]
	global_load_dwordx4 v[82:85], v[152:153], off
	v_readfirstlane_b32 s79, v150
	s_and_b64 vcc, exec, s[12:13]
	s_cbranch_vccnz .LBB0_808
	s_and_b64 vcc, exec, s[98:99]
	s_cbranch_vccnz .LBB0_808
	s_add_i32 s28, s75, 0xffffff80
	s_cmp_gt_i32 s28, s73
	s_cbranch_scc1 .LBB0_808
	s_cmp_le_i32 s48, s72
	v_add_u32_e32 v150, s78, v144
	s_mov_b64 s[66:67], -1
	v_add_u32_e32 v152, s78, v145
	v_lshl_add_u32 v153, v142, 2, s71
	s_cbranch_scc0 .LBB0_805
; #define LAS __attribute__((address_space(3)))
; __device__ __forceinline__ unsigned cvtpk(float lo, float hi) { typedef __bf16 bf16x2_t __attribute__((ext_vector_type(2))); f32x2 v = {lo, hi}; bf16x2_t b = __builtin_convertvector(v, bf16x2_t); return __builtin_bit_cast(unsigned, b); }
; template <bool BAND>
; __device__ __forceinline__ void tile_body(f32x16* o, float& l_reg, const bf16x8* qr, const LAS unsigned char* kbs, const LAS float* wb, int vb, float ci, int hi, int keybase, int qabs) {
;     f32x16 p0, p1;
; #pragma unroll
;     for (int g4 = 0; g4 < 4; ++g4) {
;         const f32x4 ba = *(const LAS f32x4*)(wb + 8 * g4 + 4 * hi) + ci, bb = *(const LAS f32x4*)(wb + 32 + 8 * g4 + 4 * hi) + ci;
; #pragma unroll
;         for (int e = 0; e < 4; ++e) { p0[4 * g4 + e] = ba[e]; p1[4 * g4 + e] = bb[e]; }
;     }
; #pragma unroll
;     for (int d0 = 0; d0 < 4; ++d0) {
;         const bf16x8 b0 = *(const LAS bf16x8*)(kbs + d0 * 2048), b1 = *(const LAS bf16x8*)(kbs + d0 * 2048 + 512);
;         p0 = __builtin_amdgcn_mfma_f32_32x32x16_bf16(b0, qr[d0], p0, 0, 0, 0); p1 = __builtin_amdgcn_mfma_f32_32x32x16_bf16(b1, qr[d0], p1, 0, 0, 0); }
;     if (BAND) {
; #pragma unroll
;         for (int r = 0; r < 16; ++r) { const int key = keybase + 8 * (r >> 2) + (r & 3); if (key > qabs) p0[r] = -INFINITY; if (key + 32 > qabs) p1[r] = -INFINITY; }
;     }
;     f32x2 s2 = {0.f, 0.f};
; #pragma unroll
;     for (int r = 0; r < 16; r += 2) {
;         p0[r] = __builtin_amdgcn_exp2f(p0[r]); p0[r + 1] = __builtin_amdgcn_exp2f(p0[r + 1]); p1[r] = __builtin_amdgcn_exp2f(p1[r]); p1[r + 1] = __builtin_amdgcn_exp2f(p1[r + 1]);
;         s2 += (f32x2){p0[r], p0[r + 1]}; s2 += (f32x2){p1[r], p1[r + 1]}; }
;     l_reg += s2.x + s2.y;
;     u32x4 pw0, pw1, pw2, pw3;
;     pw0 = (u32x4){cvtpk(p0[0], p0[1]), cvtpk(p0[2], p0[3]), cvtpk(p0[4], p0[5]), cvtpk(p0[6], p0[7])};
;     pw1 = (u32x4){cvtpk(p0[8], p0[9]), cvtpk(p0[10], p0[11]), cvtpk(p0[12], p0[13]), cvtpk(p0[14], p0[15])};
;     pw2 = (u32x4){cvtpk(p1[0], p1[1]), cvtpk(p1[2], p1[3]), cvtpk(p1[4], p1[5]), cvtpk(p1[6], p1[7])};
;     pw3 = (u32x4){cvtpk(p1[8], p1[9]), cvtpk(p1[10], p1[11]), cvtpk(p1[12], p1[13]), cvtpk(p1[14], p1[15])};
;     pv(o, vb, __builtin_bit_cast(bf16x8, pw0), __builtin_bit_cast(bf16x8, pw1), __builtin_bit_cast(bf16x8, pw2), __builtin_bit_cast(bf16x8, pw3));
	ds_read_b128 v[34:37], v153 offset:32768
	ds_read_b128 v[38:41], v153 offset:32800
	ds_read_b128 v[42:45], v153 offset:32832
	ds_read_b128 v[46:49], v153 offset:32864
	ds_read_b128 v[50:53], v153 offset:32896
	ds_read_b128 v[54:57], v153 offset:32928
	ds_read_b128 v[58:61], v153 offset:32960
	ds_read_b128 v[62:65], v153 offset:32992
	ds_read_b128 v[154:157], v152
	ds_read_b128 v[158:161], v152 offset:512
	s_waitcnt lgkmcnt(6)
	ds_read_b128 v[210:213], v152 offset:2048
	ds_read_b128 v[214:217], v152 offset:2560
	ds_read_b128 v[218:221], v152 offset:4096
	ds_read_b128 v[222:225], v152 offset:4608
	ds_read_b128 v[226:229], v152 offset:6144
	ds_read_b128 v[230:233], v152 offset:6656
	v_pk_add_f32 v[48:49], v[126:127], v[48:49]
	v_pk_add_f32 v[44:45], v[122:123], v[44:45]
	v_pk_add_f32 v[40:41], v[118:119], v[40:41]
	v_pk_add_f32 v[36:37], v[114:115], v[36:37]
	v_pk_add_f32 v[46:47], v[124:125], v[46:47]
	v_pk_add_f32 v[42:43], v[120:121], v[42:43]
	v_pk_add_f32 v[38:39], v[116:117], v[38:39]
	v_pk_add_f32 v[34:35], v[112:113], v[34:35]
	s_waitcnt lgkmcnt(8)
	v_pk_add_f32 v[64:65], v[126:127], v[64:65]
	v_pk_add_f32 v[60:61], v[122:123], v[60:61]
	s_waitcnt lgkmcnt(7)
	v_mfma_f32_32x32x16_bf16 v[34:49], v[154:157], v[94:97], v[34:49]
	v_add_f32_e64 v56, v118, v56
	v_add_f32_e64 v57, v119, v57
	v_add_f32_e64 v52, v114, v52
	v_add_f32_e64 v53, v115, v53
	v_add_f32_e64 v62, v124, v62
	v_add_f32_e64 v63, v125, v63
	v_pk_add_f32 v[58:59], v[120:121], v[58:59]
	v_pk_add_f32 v[54:55], v[116:117], v[54:55]
	v_pk_add_f32 v[50:51], v[112:113], v[50:51]
	s_waitcnt lgkmcnt(6)
	s_nop 0
	v_mfma_f32_32x32x16_bf16 v[50:65], v[158:161], v[94:97], v[50:65]
	s_waitcnt lgkmcnt(5)
	v_mfma_f32_32x32x16_bf16 v[34:49], v[210:213], v[98:101], v[34:49]
	s_waitcnt lgkmcnt(4)
	v_mfma_f32_32x32x16_bf16 v[50:65], v[214:217], v[98:101], v[50:65]
	s_waitcnt lgkmcnt(3)
	v_mfma_f32_32x32x16_bf16 v[34:49], v[218:221], v[102:105], v[34:49]
	s_waitcnt lgkmcnt(2)
	v_mfma_f32_32x32x16_bf16 v[50:65], v[222:225], v[102:105], v[50:65]
	s_waitcnt lgkmcnt(1)
	v_mfma_f32_32x32x16_bf16 v[34:49], v[226:229], v[90:93], v[34:49]
	s_waitcnt lgkmcnt(0)
	v_mfma_f32_32x32x16_bf16 v[50:65], v[230:233], v[90:93], v[50:65]
	s_nop 9
	v_exp_f32_e32 v34, v34
	v_exp_f32_e32 v35, v35
	v_exp_f32_e32 v36, v36
	v_exp_f32_e32 v37, v37
	v_exp_f32_e32 v38, v38
	v_pk_add_f32 v[154:155], v[34:35], 0 op_sel_hi:[1,0]
	v_exp_f32_e32 v39, v39
	v_exp_f32_e32 v50, v50
	v_exp_f32_e32 v51, v51
	v_exp_f32_e32 v52, v52
	v_exp_f32_e32 v53, v53
	v_exp_f32_e32 v54, v54
	v_pk_add_f32 v[154:155], v[50:51], v[154:155]
	v_exp_f32_e32 v55, v55
	v_pk_add_f32 v[154:155], v[36:37], v[154:155]
	v_exp_f32_e32 v40, v40
	v_exp_f32_e32 v41, v41
	v_pk_add_f32 v[154:155], v[52:53], v[154:155]
	v_exp_f32_e32 v56, v56
	v_exp_f32_e32 v57, v57
	v_pk_add_f32 v[154:155], v[38:39], v[154:155]
	v_exp_f32_e32 v42, v42
	v_exp_f32_e32 v43, v43
	v_pk_add_f32 v[154:155], v[54:55], v[154:155]
	v_exp_f32_e32 v58, v58
	v_exp_f32_e32 v59, v59
	v_pk_add_f32 v[154:155], v[40:41], v[154:155]
	v_exp_f32_e32 v44, v44
	v_exp_f32_e32 v45, v45
	v_pk_add_f32 v[154:155], v[56:57], v[154:155]
	v_exp_f32_e32 v60, v60
	v_exp_f32_e32 v61, v61
	v_pk_add_f32 v[154:155], v[42:43], v[154:155]
	v_exp_f32_e32 v46, v46
	v_exp_f32_e32 v47, v47
	v_cvt_pk_bf16_f32 v164, v50, v51
	ds_read_b64_tr_b16 v[50:51],v150 offset:0
	v_pk_add_f32 v[154:155], v[58:59], v[154:155]
	v_exp_f32_e32 v62, v62
	v_exp_f32_e32 v63, v63
	v_cvt_pk_bf16_f32 v165, v52, v53
	ds_read_b64_tr_b16 v[52:53],v150 offset:512
	v_pk_add_f32 v[154:155], v[44:45], v[154:155]
	v_exp_f32_e32 v48, v48
	v_exp_f32_e32 v49, v49
	v_cvt_pk_bf16_f32 v166, v54, v55
	ds_read_b64_tr_b16 v[54:55],v150 offset:1024
	v_pk_add_f32 v[154:155], v[60:61], v[154:155]
	v_exp_f32_e32 v64, v64
	v_exp_f32_e32 v65, v65
	v_cvt_pk_bf16_f32 v167, v56, v57
	ds_read_b64_tr_b16 v[56:57],v150 offset:1536
	v_pk_add_f32 v[154:155], v[46:47], v[154:155]
	v_cvt_pk_bf16_f32 v168, v58, v59
	ds_read_b64_tr_b16 v[58:59],v150 offset:2048
	v_pk_add_f32 v[154:155], v[62:63], v[154:155]
	v_cvt_pk_bf16_f32 v169, v60, v61
	ds_read_b64_tr_b16 v[60:61],v150 offset:2560
	v_pk_add_f32 v[154:155], v[48:49], v[154:155]
	v_cvt_pk_bf16_f32 v170, v62, v63
	ds_read_b64_tr_b16 v[62:63],v150 offset:3072
	v_pk_add_f32 v[154:155], v[64:65], v[154:155]
	v_cvt_pk_bf16_f32 v171, v64, v65
	ds_read_b64_tr_b16 v[64:65],v150 offset:3584
	s_waitcnt lgkmcnt(0)
	v_add_f32_e32 v154, v154, v155
	v_add_f32_e32 v154, v148, v154
	v_cvt_pk_bf16_f32 v156, v34, v35
	v_cvt_pk_bf16_f32 v157, v36, v37
	v_cvt_pk_bf16_f32 v158, v38, v39
	v_cvt_pk_bf16_f32 v159, v40, v41
	v_cvt_pk_bf16_f32 v160, v42, v43
	v_cvt_pk_bf16_f32 v161, v44, v45
	v_cvt_pk_bf16_f32 v162, v46, v47
	v_cvt_pk_bf16_f32 v163, v48, v49
	v_mfma_f32_32x32x16_bf16 v[2:17], v[156:159], v[50:53], v[2:17]
	ds_read_b64_tr_b16 v[172:173],v150 offset:4096
	ds_read_b64_tr_b16 v[174:175],v150 offset:4608
	ds_read_b64_tr_b16 v[176:177],v150 offset:5120
	ds_read_b64_tr_b16 v[178:179],v150 offset:5632
	ds_read_b64_tr_b16 v[180:181],v150 offset:6144
	ds_read_b64_tr_b16 v[182:183],v150 offset:6656
	ds_read_b64_tr_b16 v[184:185],v150 offset:7168
	s_nop 0
	v_mfma_f32_32x32x16_bf16 v[2:17], v[160:163], v[54:57], v[2:17]
	ds_read_b64_tr_b16 v[186:187],v150 offset:7680
	s_waitcnt lgkmcnt(0)
	v_mfma_f32_32x32x16_bf16 v[2:17], v[164:167], v[58:61], v[2:17]
	v_mfma_f32_32x32x16_bf16 v[2:17], v[168:171], v[62:65], v[2:17]
	v_mfma_f32_32x32x16_bf16 v[18:33], v[156:159], v[172:175], v[18:33]
	s_mov_b64 s[66:67], 0
	v_mfma_f32_32x32x16_bf16 v[18:33], v[160:163], v[176:179], v[18:33]
	v_mfma_f32_32x32x16_bf16 v[18:33], v[164:167], v[180:183], v[18:33]
	v_mfma_f32_32x32x16_bf16 v[18:33], v[168:171], v[184:187], v[18:33]

; #define DPP_SHL(v, n) __builtin_bit_cast(float, __builtin_amdgcn_update_dpp(0, __builtin_bit_cast(int, (v)), 0x100 | (n), 0xF, 0xF, true))
; __device__ __forceinline__ float suffix_incl(float v, int lane) {
;     v += DPP_SHL(v, 1); v += DPP_SHL(v, 2); v += DPP_SHL(v, 4); v += DPP_SHL(v, 8);
;     const float t1 = __builtin_bit_cast(float, __builtin_amdgcn_readlane(__builtin_bit_cast(int, v), 16)), t2 = __builtin_bit_cast(float, __builtin_amdgcn_readlane(__builtin_bit_cast(int, v), 32)),
;                 t3 = __builtin_bit_cast(float, __builtin_amdgcn_readlane(__builtin_bit_cast(int, v), 48));
;     const int row = lane >> 4;
;     const float add = (row == 0) ? (t1 + t2) + t3 : (row == 1) ? t2 + t3 : (row == 2) ? t3 : 0.f;
;     return v + add;
.LBB0_808:
	s_cmp_lg_u32 s48, 1
	v_fma_f32 v150, v151, s50, -v146
	s_cselect_b64 s[66:67], -1, 0
	v_cmp_nlt_f32_e64 s[68:69], v150, -v131
	v_fma_f32 v196, v151, s50, -v197
	v_cmp_lt_f32_e64 s[100:101], v196, -v131
	s_nop 3
	s_or_b64 s[98:99], s[98:99], s[100:101]
	s_and_b64 s[70:71], s[66:67], s[68:69]
	s_mov_b64 s[68:69], -1
	s_and_saveexec_b64 s[66:67], s[70:71]
	s_cbranch_execz .LBB0_775
	s_waitcnt lgkmcnt(0)
	s_barrier
	s_waitcnt vmcnt(8)
	s_nop 1
	v_add_f32_dpp v150, v139, v139 row_shl:1 row_mask:0xf bank_mask:0xf bound_ctrl:1
	s_nop 1
	v_add_f32_dpp v150, v150, v150 row_shl:2 row_mask:0xf bank_mask:0xf bound_ctrl:1
	s_nop 1
	v_add_f32_dpp v150, v150, v150 row_shl:4 row_mask:0xf bank_mask:0xf bound_ctrl:1
	s_nop 1
	v_add_f32_dpp v150, v150, v150 row_shl:8 row_mask:0xf bank_mask:0xf bound_ctrl:1
	s_nop 0
	v_readlane_b32 s28, v150, 16
	v_readlane_b32 s80, v150, 32
	v_readlane_b32 s78, v150, 48
	s_nop 0
	v_mul_f32_e32 v152, s80, v192
	v_fmac_f32_e32 v152, s28, v191
	v_fmac_f32_e32 v152, s78, v193
	v_add_f32_e32 v151, s79, v151
	v_add_f32_e32 v150, v150, v152
	v_add_f32_e32 v152, v151, v150
	v_sub_f32_e32 v139, v152, v139
	v_mul_f32_e32 v139, 0x3fb8aa3b, v139
	s_max_i32 s28, s48, 6
	ds_write_b32 v0, v139 offset:32768
	s_waitcnt vmcnt(4)
	ds_write_b128 v149, v[78:81]
	ds_write_b128 v149, v[86:89] offset:8192
	s_add_i32 s28, s28, -6
	s_waitcnt lgkmcnt(0)
	s_lshl_b64 s[68:69], s[28:29], 11
	v_lshl_add_u64 v[78:79], v[110:111], 0, s[68:69]
	global_load_dword v139, v[78:79], off
	s_lshl_b64 s[68:69], s[28:29], 16
	v_lshl_add_u64 v[86:87], v[106:107], 0, s[68:69]
	global_load_dwordx4 v[78:81], v[86:87], off
	v_lshl_add_u64 v[152:153], v[108:109], 0, s[68:69]
	global_load_dwordx4 v[86:89], v[152:153], off
	v_readfirstlane_b32 s70, v150
	s_andn2_b64 vcc, exec, s[60:61]
	s_mov_b64 s[68:69], -1
	s_cbranch_vccnz .LBB0_819
	s_add_i32 s28, s75, 0xffffff40
	s_mov_b64 s[68:69], 0
